# lever 7 address arithmetic: attention K-tile row address via s_mul_i32 + v_lshl_add_u64 instead of two v_mad_u64_u32 per step (on v52)
# baseline (speedup 1.0000x reference)
.LBB0_205:
	s_add_i32 s17, s15, -1
	s_cmp_lt_u32 s17, s12
	s_cselect_b64 s[6:7], -1, 0
	s_and_b64 s[8:9], s[6:7], exec
	s_cselect_b32 s4, s17, s14
	s_lshl_b32 s4, s4, 6
	s_add_i32 s18, s15, -2
	s_or_b32 s19, s4, 32
	s_cmp_lt_u32 s18, s12
	s_cselect_b64 s[8:9], -1, 0
	s_mul_i32 s10, s4, 0x600
	s_mov_b32 s11, s5
	v_lshl_add_u64 v[144:145], s[10:11], 0, v[194:195]
	s_mul_i32 s10, s19, 0x600
	v_lshl_add_u64 v[148:149], s[10:11], 0, v[194:195]
	s_and_b64 s[10:11], s[8:9], exec
	s_cselect_b32 s10, s18, s14
	s_lshl_b32 s10, s10, 6
	s_mov_b32 s11, s5
	v_lshl_add_u64 v[152:153], s[10:11], 1, v[196:197]
	v_add_co_u32_e32 v154, vcc, 0x80000, v152
	global_load_dwordx4 v[144:147], v[144:145], off
	s_nop 0
	global_load_dwordx4 v[148:151], v[148:149], off
	v_addc_co_u32_e32 v155, vcc, 0, v153, vcc
	global_load_dwordx4 v[156:159], v[152:153], off
	s_nop 0
	global_load_dwordx4 v[152:155], v[154:155], off
	s_sub_i32 s10, s13, 30
	v_cmp_le_u32_e32 vcc, s10, v212
	s_and_b64 s[10:11], s[8:9], vcc
	s_and_saveexec_b64 s[8:9], s[10:11]
	s_cbranch_execz .LBB0_207
	s_mul_i32 s10, s24, 0x4400
	s_setprio 1
	v_add3_u32 v162, v203, s10, v204
	ds_read_b128 v[112:115], v162
	ds_read_b128 v[116:119], v162 offset:32
	ds_read_b128 v[120:123], v162 offset:64
	ds_read_b128 v[124:127], v162 offset:96
	ds_read_b128 v[222:225], v162 offset:8704
	ds_read_b128 v[236:239], v162 offset:8736
	ds_read_b128 v[240:243], v162 offset:8768
	ds_read_b128 v[244:247], v162 offset:8800
	s_waitcnt lgkmcnt(7)
	v_mfma_f32_32x32x16_bf16 v[96:111], v[112:115], v[128:131], 0
	s_waitcnt lgkmcnt(6)
	v_mfma_f32_32x32x16_bf16 v[96:111], v[116:119], v[132:135], v[96:111]
	s_waitcnt lgkmcnt(5)
	v_mfma_f32_32x32x16_bf16 v[96:111], v[120:123], v[136:139], v[96:111]
	s_waitcnt lgkmcnt(4)
	v_mfma_f32_32x32x16_bf16 v[96:111], v[124:127], v[140:143], v[96:111]
	s_waitcnt lgkmcnt(3)
	v_mfma_f32_32x32x16_bf16 v[112:127], v[222:225], v[128:131], 0
	s_waitcnt lgkmcnt(2)
	v_mfma_f32_32x32x16_bf16 v[112:127], v[236:239], v[132:135], v[112:127]
	s_waitcnt lgkmcnt(1)
	v_mfma_f32_32x32x16_bf16 v[112:127], v[240:243], v[136:139], v[112:127]
	s_waitcnt lgkmcnt(0)
	v_mfma_f32_32x32x16_bf16 v[112:127], v[244:247], v[140:143], v[112:127]
	s_setprio 0

.LBB0_213:
	s_or_b64 exec, exec, s[8:9]
	s_mul_i32 s8, s16, 0x4400
	v_add_u32_e32 v162, s8, v175
	s_cmp_lt_u32 s15, s12
	s_waitcnt vmcnt(3)
	ds_write_b128 v162, v[144:147]
	s_waitcnt vmcnt(2)
	ds_write_b128 v162, v[148:151] offset:8704
	s_waitcnt vmcnt(1)
	ds_write2_b64 v208, v[156:157], v[158:159] offset1:2
	v_add_u32_e32 v144, 0x2000, v208
	s_cselect_b32 s9, s15, s14
	s_waitcnt vmcnt(0)
	ds_write2_b64 v144, v[152:153], v[154:155] offset0:128 offset1:130
	s_lshl_b32 s9, s9, 6
	v_lshl_add_u64 v[152:153], s[4:5], 1, v[196:197]
	s_mul_i32 s10, s9, 0x600
	s_mov_b32 s11, s5
	v_lshl_add_u64 v[144:145], s[10:11], 0, v[194:195]
	s_or_b32 s9, s9, 32
	v_add_co_u32_e32 v154, vcc, 0x80000, v152
	s_mul_i32 s10, s9, 0x600
	v_lshl_add_u64 v[148:149], s[10:11], 0, v[194:195]
	s_nop 0
	v_addc_co_u32_e32 v155, vcc, 0, v153, vcc
	s_waitcnt lgkmcnt(0)
	s_barrier
	global_load_dwordx4 v[144:147], v[144:145], off
	s_nop 0
	global_load_dwordx4 v[148:151], v[148:149], off
	s_nop 0
	global_load_dwordx4 v[156:159], v[152:153], off
	s_nop 0
	global_load_dwordx4 v[152:155], v[154:155], off
	s_add_i32 s4, s13, 34
	v_cmp_le_u32_e32 vcc, s4, v212
	s_and_b64 s[10:11], s[6:7], vcc
	s_and_saveexec_b64 s[6:7], s[10:11]
	s_cbranch_execz .LBB0_215
	s_setprio 1
	v_add3_u32 v162, v203, s8, v204
	ds_read_b128 v[80:83], v162
	ds_read_b128 v[84:87], v162 offset:32
	ds_read_b128 v[88:91], v162 offset:64
	ds_read_b128 v[92:95], v162 offset:96
	ds_read_b128 v[222:225], v162 offset:8704
	ds_read_b128 v[236:239], v162 offset:8736
	ds_read_b128 v[240:243], v162 offset:8768
	ds_read_b128 v[244:247], v162 offset:8800
	s_waitcnt lgkmcnt(7)
	v_mfma_f32_32x32x16_bf16 v[64:79], v[80:83], v[128:131], 0
	s_waitcnt lgkmcnt(6)
	v_mfma_f32_32x32x16_bf16 v[64:79], v[84:87], v[132:135], v[64:79]
	s_waitcnt lgkmcnt(5)
	v_mfma_f32_32x32x16_bf16 v[64:79], v[88:91], v[136:139], v[64:79]
	s_waitcnt lgkmcnt(4)
	v_mfma_f32_32x32x16_bf16 v[64:79], v[92:95], v[140:143], v[64:79]
	s_waitcnt lgkmcnt(3)
	v_mfma_f32_32x32x16_bf16 v[80:95], v[222:225], v[128:131], 0
	s_waitcnt lgkmcnt(2)
	v_mfma_f32_32x32x16_bf16 v[80:95], v[236:239], v[132:135], v[80:95]
	s_waitcnt lgkmcnt(1)
	v_mfma_f32_32x32x16_bf16 v[80:95], v[240:243], v[136:139], v[80:95]
	s_waitcnt lgkmcnt(0)
	v_mfma_f32_32x32x16_bf16 v[80:95], v[244:247], v[140:143], v[80:95]
	s_setprio 0
